# v58: final RMSNorm folded into the last residual epilogue as well (x_new never stored un-normalised; FINAL step removed)
# speedup vs baseline: 1.0737x; 1.0073x over previous
.LBB0_8:
	v_readlane_b32 s6, v254, 61
	s_add_i32 s6, s6, 1
	s_cmp_eq_u32 s6, 36
	v_readlane_b32 s7, v254, 62
	s_cbranch_scc0 .LBB0_9
	s_getpc_b64 s[98:99]

.Lres_src:
	s_lshl_b32 s2, s48, 8
	s_or_b32 s2, s2, s68
	v_lshl_add_u32 v250, v239, 2, s2
	v_lshlrev_b32_e32 v250, 2, v250
	v_lshlrev_b32_e32 v249, 12, v186
	v_add_u32_e32 v248, v249, v250
	s_nop 2
	global_load_dwordx4 v[216:219], v250, s[8:9] offset:0
	global_load_dwordx4 v[220:223], v250, s[8:9] offset:64
	global_load_dwordx4 v[240:243], v250, s[8:9] offset:512
	global_load_dwordx4 v[244:247], v250, s[8:9] offset:576
	v_readlane_b32 s3, v254, 61
	s_mov_b32 s2, -1
	s_cmp_eq_u32 s3, 8
	s_cselect_b32 s2, 2, s2
	s_cmp_eq_u32 s3, 10
	s_cselect_b32 s2, 4, s2
	s_cmp_eq_u32 s3, 20
	s_cselect_b32 s2, 8, s2
	s_cmp_eq_u32 s3, 22
	s_cselect_b32 s2, 9, s2
	s_cmp_eq_u32 s3, 26
	s_cselect_b32 s2, 10, s2
	s_cmp_eq_u32 s3, 28
	s_cselect_b32 s2, 12, s2
	s_cmp_eq_u32 s3, 30
	s_cselect_b32 s2, 13, s2
	s_cmp_eq_u32 s3, 33
	s_cselect_b32 s2, 14, s2
	s_cmp_eq_u32 s3, 35
	s_cselect_b32 s2, 99, s2
	s_mov_b32 s100, s2
	s_cmp_lt_i32 s2, 0
	s_cbranch_scc0 .Lrf_fused
	global_load_dwordx4 v[130:133], v248, s[10:11] offset:0
	s_add_u32 s14, s10, 0x10000
	s_addc_u32 s15, s11, 0
	global_load_dwordx4 v[134:137], v248, s[14:15] offset:0
	s_add_u32 s14, s10, 0x20000
	s_addc_u32 s15, s11, 0
	global_load_dwordx4 v[138:141], v248, s[14:15] offset:0
	s_add_u32 s14, s10, 0x30000
	s_addc_u32 s15, s11, 0
	global_load_dwordx4 v[142:145], v248, s[14:15] offset:0
	s_add_u32 s14, s10, 0x80000
	s_addc_u32 s15, s11, 0
	global_load_dwordx4 v[146:149], v248, s[14:15] offset:0
	s_add_u32 s14, s10, 0x90000
	s_addc_u32 s15, s11, 0
	global_load_dwordx4 v[150:153], v248, s[14:15] offset:0
	s_add_u32 s14, s10, 0xa0000
	s_addc_u32 s15, s11, 0
	global_load_dwordx4 v[154:157], v248, s[14:15] offset:0
	s_add_u32 s14, s10, 0xb0000
	s_addc_u32 s15, s11, 0
	global_load_dwordx4 v[158:161], v248, s[14:15] offset:0
	global_load_dwordx4 v[162:165], v248, s[10:11] offset:64
	s_add_u32 s14, s10, 0x10000
	s_addc_u32 s15, s11, 0
	global_load_dwordx4 v[188:191], v248, s[14:15] offset:64
	s_add_u32 s14, s10, 0x20000
	s_addc_u32 s15, s11, 0
	global_load_dwordx4 v[192:195], v248, s[14:15] offset:64
	s_add_u32 s14, s10, 0x30000
	s_addc_u32 s15, s11, 0
	global_load_dwordx4 v[196:199], v248, s[14:15] offset:64
	s_add_u32 s14, s10, 0x80000
	s_addc_u32 s15, s11, 0
	global_load_dwordx4 v[200:203], v248, s[14:15] offset:64
	s_add_u32 s14, s10, 0x90000
	s_addc_u32 s15, s11, 0
	global_load_dwordx4 v[204:207], v248, s[14:15] offset:64
	s_add_u32 s14, s10, 0xa0000
	s_addc_u32 s15, s11, 0
	global_load_dwordx4 v[208:211], v248, s[14:15] offset:64
	s_add_u32 s14, s10, 0xb0000
	s_addc_u32 s15, s11, 0
	global_load_dwordx4 v[212:215], v248, s[14:15] offset:64
	s_waitcnt vmcnt(12)
	v_pk_mul_f32 v[216:217], s[28:29], v[216:217]
	v_pk_mul_f32 v[218:219], s[28:29], v[218:219]
	v_pk_mul_f32 v[220:221], s[28:29], v[220:221]
	v_pk_mul_f32 v[222:223], s[28:29], v[222:223]
	v_pk_mul_f32 v[240:241], s[28:29], v[240:241]
	v_pk_mul_f32 v[242:243], s[28:29], v[242:243]
	v_pk_mul_f32 v[244:245], s[28:29], v[244:245]
	v_pk_mul_f32 v[246:247], s[28:29], v[246:247]
	v_pk_fma_f32 v[130:131], v[216:217], v[126:127], v[130:131]
	v_pk_fma_f32 v[132:133], v[218:219], v[128:129], v[132:133]
	v_pk_fma_f32 v[134:135], v[216:217], v[110:111], v[134:135]
	v_pk_fma_f32 v[136:137], v[218:219], v[112:113], v[136:137]
	v_pk_fma_f32 v[138:139], v[216:217], v[94:95], v[138:139]
	v_pk_fma_f32 v[140:141], v[218:219], v[96:97], v[140:141]
	v_pk_fma_f32 v[142:143], v[216:217], v[78:79], v[142:143]
	v_pk_fma_f32 v[144:145], v[218:219], v[80:81], v[144:145]
	global_store_dwordx4 v248, v[130:133], s[12:13] offset:0
	s_add_u32 s2, s12, 0x10000
	s_addc_u32 s3, s13, 0
	global_store_dwordx4 v248, v[134:137], s[2:3] offset:0
	s_add_u32 s2, s12, 0x20000
	s_addc_u32 s3, s13, 0
	global_store_dwordx4 v248, v[138:141], s[2:3] offset:0
	s_add_u32 s2, s12, 0x30000
	s_addc_u32 s3, s13, 0
	global_store_dwordx4 v248, v[142:145], s[2:3] offset:0
	global_load_dwordx4 v[130:133], v248, s[10:11] offset:512
	s_add_u32 s14, s10, 0x10000
	s_addc_u32 s15, s11, 0
	global_load_dwordx4 v[134:137], v248, s[14:15] offset:512
	s_add_u32 s14, s10, 0x20000
	s_addc_u32 s15, s11, 0
	global_load_dwordx4 v[138:141], v248, s[14:15] offset:512
	s_add_u32 s14, s10, 0x30000
	s_addc_u32 s15, s11, 0
	global_load_dwordx4 v[142:145], v248, s[14:15] offset:512
	s_waitcnt vmcnt(16)
	v_pk_fma_f32 v[146:147], v[216:217], v[62:63], v[146:147]
	v_pk_fma_f32 v[148:149], v[218:219], v[64:65], v[148:149]
	v_pk_fma_f32 v[150:151], v[216:217], v[46:47], v[150:151]
	v_pk_fma_f32 v[152:153], v[218:219], v[48:49], v[152:153]
	v_pk_fma_f32 v[154:155], v[216:217], v[30:31], v[154:155]
	v_pk_fma_f32 v[156:157], v[218:219], v[32:33], v[156:157]
	v_pk_fma_f32 v[158:159], v[216:217], v[14:15], v[158:159]
	v_pk_fma_f32 v[160:161], v[218:219], v[16:17], v[160:161]
	s_add_u32 s2, s12, 0x80000
	s_addc_u32 s3, s13, 0
	global_store_dwordx4 v248, v[146:149], s[2:3] offset:0
	s_add_u32 s2, s12, 0x90000
	s_addc_u32 s3, s13, 0
	global_store_dwordx4 v248, v[150:153], s[2:3] offset:0
	s_add_u32 s2, s12, 0xa0000
	s_addc_u32 s3, s13, 0
	global_store_dwordx4 v248, v[154:157], s[2:3] offset:0
	s_add_u32 s2, s12, 0xb0000
	s_addc_u32 s3, s13, 0
	global_store_dwordx4 v248, v[158:161], s[2:3] offset:0
	s_add_u32 s14, s10, 0x80000
	s_addc_u32 s15, s11, 0
	global_load_dwordx4 v[146:149], v248, s[14:15] offset:512
	s_add_u32 s14, s10, 0x90000
	s_addc_u32 s15, s11, 0
	global_load_dwordx4 v[150:153], v248, s[14:15] offset:512
	s_add_u32 s14, s10, 0xa0000
	s_addc_u32 s15, s11, 0
	global_load_dwordx4 v[154:157], v248, s[14:15] offset:512
	s_add_u32 s14, s10, 0xb0000
	s_addc_u32 s15, s11, 0
	global_load_dwordx4 v[158:161], v248, s[14:15] offset:512
	s_waitcnt vmcnt(20)
	v_pk_fma_f32 v[162:163], v[220:221], v[122:123], v[162:163]
	v_pk_fma_f32 v[164:165], v[222:223], v[124:125], v[164:165]
	v_pk_fma_f32 v[188:189], v[220:221], v[106:107], v[188:189]
	v_pk_fma_f32 v[190:191], v[222:223], v[108:109], v[190:191]
	v_pk_fma_f32 v[192:193], v[220:221], v[90:91], v[192:193]
	v_pk_fma_f32 v[194:195], v[222:223], v[92:93], v[194:195]
	v_pk_fma_f32 v[196:197], v[220:221], v[74:75], v[196:197]
	v_pk_fma_f32 v[198:199], v[222:223], v[76:77], v[198:199]
	global_store_dwordx4 v248, v[162:165], s[12:13] offset:64
	s_add_u32 s2, s12, 0x10000
	s_addc_u32 s3, s13, 0
	global_store_dwordx4 v248, v[188:191], s[2:3] offset:64
	s_add_u32 s2, s12, 0x20000
	s_addc_u32 s3, s13, 0
	global_store_dwordx4 v248, v[192:195], s[2:3] offset:64
	s_add_u32 s2, s12, 0x30000
	s_addc_u32 s3, s13, 0
	global_store_dwordx4 v248, v[196:199], s[2:3] offset:64
	global_load_dwordx4 v[162:165], v248, s[10:11] offset:576
	s_add_u32 s14, s10, 0x10000
	s_addc_u32 s15, s11, 0
	global_load_dwordx4 v[188:191], v248, s[14:15] offset:576
	s_add_u32 s14, s10, 0x20000
	s_addc_u32 s15, s11, 0
	global_load_dwordx4 v[192:195], v248, s[14:15] offset:576
	s_add_u32 s14, s10, 0x30000
	s_addc_u32 s15, s11, 0
	global_load_dwordx4 v[196:199], v248, s[14:15] offset:576
	s_waitcnt vmcnt(24)
	v_pk_fma_f32 v[200:201], v[220:221], v[58:59], v[200:201]
	v_pk_fma_f32 v[202:203], v[222:223], v[60:61], v[202:203]
	v_pk_fma_f32 v[204:205], v[220:221], v[42:43], v[204:205]
	v_pk_fma_f32 v[206:207], v[222:223], v[44:45], v[206:207]
	v_pk_fma_f32 v[208:209], v[220:221], v[26:27], v[208:209]
	v_pk_fma_f32 v[210:211], v[222:223], v[28:29], v[210:211]
	v_pk_fma_f32 v[212:213], v[220:221], v[10:11], v[212:213]
	v_pk_fma_f32 v[214:215], v[222:223], v[12:13], v[214:215]
	s_add_u32 s2, s12, 0x80000
	s_addc_u32 s3, s13, 0
	global_store_dwordx4 v248, v[200:203], s[2:3] offset:64
	s_add_u32 s2, s12, 0x90000
	s_addc_u32 s3, s13, 0
	global_store_dwordx4 v248, v[204:207], s[2:3] offset:64
	s_add_u32 s2, s12, 0xa0000
	s_addc_u32 s3, s13, 0
	global_store_dwordx4 v248, v[208:211], s[2:3] offset:64
	s_add_u32 s2, s12, 0xb0000
	s_addc_u32 s3, s13, 0
	global_store_dwordx4 v248, v[212:215], s[2:3] offset:64
	s_add_u32 s14, s10, 0x80000
	s_addc_u32 s15, s11, 0
	global_load_dwordx4 v[200:203], v248, s[14:15] offset:576
	s_add_u32 s14, s10, 0x90000
	s_addc_u32 s15, s11, 0
	global_load_dwordx4 v[204:207], v248, s[14:15] offset:576
	s_add_u32 s14, s10, 0xa0000
	s_addc_u32 s15, s11, 0
	global_load_dwordx4 v[208:211], v248, s[14:15] offset:576
	s_add_u32 s14, s10, 0xb0000
	s_addc_u32 s15, s11, 0
	global_load_dwordx4 v[212:215], v248, s[14:15] offset:576
	s_waitcnt vmcnt(24)
	v_pk_fma_f32 v[130:131], v[240:241], v[118:119], v[130:131]
	v_pk_fma_f32 v[132:133], v[242:243], v[120:121], v[132:133]
	v_pk_fma_f32 v[134:135], v[240:241], v[102:103], v[134:135]
	v_pk_fma_f32 v[136:137], v[242:243], v[104:105], v[136:137]
	v_pk_fma_f32 v[138:139], v[240:241], v[86:87], v[138:139]
	v_pk_fma_f32 v[140:141], v[242:243], v[88:89], v[140:141]
	v_pk_fma_f32 v[142:143], v[240:241], v[70:71], v[142:143]
	v_pk_fma_f32 v[144:145], v[242:243], v[72:73], v[144:145]
	global_store_dwordx4 v248, v[130:133], s[12:13] offset:512
	s_add_u32 s2, s12, 0x10000
	s_addc_u32 s3, s13, 0
	global_store_dwordx4 v248, v[134:137], s[2:3] offset:512
	s_add_u32 s2, s12, 0x20000
	s_addc_u32 s3, s13, 0
	global_store_dwordx4 v248, v[138:141], s[2:3] offset:512
	s_add_u32 s2, s12, 0x30000
	s_addc_u32 s3, s13, 0
	global_store_dwordx4 v248, v[142:145], s[2:3] offset:512
	s_waitcnt vmcnt(20)
	v_pk_fma_f32 v[146:147], v[240:241], v[54:55], v[146:147]
	v_pk_fma_f32 v[148:149], v[242:243], v[56:57], v[148:149]
	v_pk_fma_f32 v[150:151], v[240:241], v[38:39], v[150:151]
	v_pk_fma_f32 v[152:153], v[242:243], v[40:41], v[152:153]
	v_pk_fma_f32 v[154:155], v[240:241], v[22:23], v[154:155]
	v_pk_fma_f32 v[156:157], v[242:243], v[24:25], v[156:157]
	v_pk_fma_f32 v[158:159], v[240:241], v[6:7], v[158:159]
	v_pk_fma_f32 v[160:161], v[242:243], v[8:9], v[160:161]
	s_add_u32 s2, s12, 0x80000
	s_addc_u32 s3, s13, 0
	global_store_dwordx4 v248, v[146:149], s[2:3] offset:512
	s_add_u32 s2, s12, 0x90000
	s_addc_u32 s3, s13, 0
	global_store_dwordx4 v248, v[150:153], s[2:3] offset:512
	s_add_u32 s2, s12, 0xa0000
	s_addc_u32 s3, s13, 0
	global_store_dwordx4 v248, v[154:157], s[2:3] offset:512
	s_add_u32 s2, s12, 0xb0000
	s_addc_u32 s3, s13, 0
	global_store_dwordx4 v248, v[158:161], s[2:3] offset:512
	s_waitcnt vmcnt(16)
	v_pk_fma_f32 v[162:163], v[244:245], v[114:115], v[162:163]
	v_pk_fma_f32 v[164:165], v[246:247], v[116:117], v[164:165]
	v_pk_fma_f32 v[188:189], v[244:245], v[98:99], v[188:189]
	v_pk_fma_f32 v[190:191], v[246:247], v[100:101], v[190:191]
	v_pk_fma_f32 v[192:193], v[244:245], v[82:83], v[192:193]
	v_pk_fma_f32 v[194:195], v[246:247], v[84:85], v[194:195]
	v_pk_fma_f32 v[196:197], v[244:245], v[66:67], v[196:197]
	v_pk_fma_f32 v[198:199], v[246:247], v[68:69], v[198:199]
	global_store_dwordx4 v248, v[162:165], s[12:13] offset:576
	s_add_u32 s2, s12, 0x10000
	s_addc_u32 s3, s13, 0
	global_store_dwordx4 v248, v[188:191], s[2:3] offset:576
	s_add_u32 s2, s12, 0x20000
	s_addc_u32 s3, s13, 0
	global_store_dwordx4 v248, v[192:195], s[2:3] offset:576
	s_add_u32 s2, s12, 0x30000
	s_addc_u32 s3, s13, 0
	global_store_dwordx4 v248, v[196:199], s[2:3] offset:576
	s_waitcnt vmcnt(12)
	v_pk_fma_f32 v[200:201], v[244:245], v[50:51], v[200:201]
	v_pk_fma_f32 v[202:203], v[246:247], v[52:53], v[202:203]
	v_pk_fma_f32 v[204:205], v[244:245], v[34:35], v[204:205]
	v_pk_fma_f32 v[206:207], v[246:247], v[36:37], v[206:207]
	v_pk_fma_f32 v[208:209], v[244:245], v[18:19], v[208:209]
	v_pk_fma_f32 v[210:211], v[246:247], v[20:21], v[210:211]
	v_pk_fma_f32 v[212:213], v[244:245], v[2:3], v[212:213]
	v_pk_fma_f32 v[214:215], v[246:247], v[4:5], v[214:215]
	s_add_u32 s2, s12, 0x80000
	s_addc_u32 s3, s13, 0
	global_store_dwordx4 v248, v[200:203], s[2:3] offset:576
	s_add_u32 s2, s12, 0x90000
	s_addc_u32 s3, s13, 0
	global_store_dwordx4 v248, v[204:207], s[2:3] offset:576
	s_add_u32 s2, s12, 0xa0000
	s_addc_u32 s3, s13, 0
	global_store_dwordx4 v248, v[208:211], s[2:3] offset:576
	s_add_u32 s2, s12, 0xb0000
	s_addc_u32 s3, s13, 0
	global_store_dwordx4 v248, v[212:215], s[2:3] offset:576
	s_branch .LBB0_561
.Lrf_fused:
	global_load_dwordx4 v[130:133], v248, s[10:11] offset:0
	s_add_u32 s14, s10, 0x10000
	s_addc_u32 s15, s11, 0
	global_load_dwordx4 v[134:137], v248, s[14:15] offset:0
	s_add_u32 s14, s10, 0x20000
	s_addc_u32 s15, s11, 0
	global_load_dwordx4 v[138:141], v248, s[14:15] offset:0
	s_add_u32 s14, s10, 0x30000
	s_addc_u32 s15, s11, 0
	global_load_dwordx4 v[142:145], v248, s[14:15] offset:0
	s_add_u32 s14, s10, 0x80000
	s_addc_u32 s15, s11, 0
	global_load_dwordx4 v[146:149], v248, s[14:15] offset:0
	s_add_u32 s14, s10, 0x90000
	s_addc_u32 s15, s11, 0
	global_load_dwordx4 v[150:153], v248, s[14:15] offset:0
	s_add_u32 s14, s10, 0xa0000
	s_addc_u32 s15, s11, 0
	global_load_dwordx4 v[154:157], v248, s[14:15] offset:0
	s_add_u32 s14, s10, 0xb0000
	s_addc_u32 s15, s11, 0
	global_load_dwordx4 v[158:161], v248, s[14:15] offset:0
	global_load_dwordx4 v[162:165], v248, s[10:11] offset:64
	s_add_u32 s14, s10, 0x10000
	s_addc_u32 s15, s11, 0
	global_load_dwordx4 v[188:191], v248, s[14:15] offset:64
	s_add_u32 s14, s10, 0x20000
	s_addc_u32 s15, s11, 0
	global_load_dwordx4 v[192:195], v248, s[14:15] offset:64
	s_add_u32 s14, s10, 0x30000
	s_addc_u32 s15, s11, 0
	global_load_dwordx4 v[196:199], v248, s[14:15] offset:64
	s_add_u32 s14, s10, 0x80000
	s_addc_u32 s15, s11, 0
	global_load_dwordx4 v[200:203], v248, s[14:15] offset:64
	s_add_u32 s14, s10, 0x90000
	s_addc_u32 s15, s11, 0
	global_load_dwordx4 v[204:207], v248, s[14:15] offset:64
	s_add_u32 s14, s10, 0xa0000
	s_addc_u32 s15, s11, 0
	global_load_dwordx4 v[208:211], v248, s[14:15] offset:64
	s_add_u32 s14, s10, 0xb0000
	s_addc_u32 s15, s11, 0
	global_load_dwordx4 v[212:215], v248, s[14:15] offset:64
	s_waitcnt vmcnt(12)
	v_pk_mul_f32 v[216:217], s[28:29], v[216:217]
	v_pk_mul_f32 v[218:219], s[28:29], v[218:219]
	v_pk_mul_f32 v[220:221], s[28:29], v[220:221]
	v_pk_mul_f32 v[222:223], s[28:29], v[222:223]
	v_pk_mul_f32 v[240:241], s[28:29], v[240:241]
	v_pk_mul_f32 v[242:243], s[28:29], v[242:243]
	v_pk_mul_f32 v[244:245], s[28:29], v[244:245]
	v_pk_mul_f32 v[246:247], s[28:29], v[246:247]
	v_pk_fma_f32 v[126:127], v[216:217], v[126:127], v[130:131]
	v_pk_fma_f32 v[128:129], v[218:219], v[128:129], v[132:133]
	v_pk_fma_f32 v[110:111], v[216:217], v[110:111], v[134:135]
	v_pk_fma_f32 v[112:113], v[218:219], v[112:113], v[136:137]
	v_pk_fma_f32 v[94:95], v[216:217], v[94:95], v[138:139]
	v_pk_fma_f32 v[96:97], v[218:219], v[96:97], v[140:141]
	v_pk_fma_f32 v[78:79], v[216:217], v[78:79], v[142:143]
	v_pk_fma_f32 v[80:81], v[218:219], v[80:81], v[144:145]
	global_load_dwordx4 v[130:133], v248, s[10:11] offset:512
	s_add_u32 s14, s10, 0x10000
	s_addc_u32 s15, s11, 0
	global_load_dwordx4 v[134:137], v248, s[14:15] offset:512
	s_add_u32 s14, s10, 0x20000
	s_addc_u32 s15, s11, 0
	global_load_dwordx4 v[138:141], v248, s[14:15] offset:512
	s_add_u32 s14, s10, 0x30000
	s_addc_u32 s15, s11, 0
	global_load_dwordx4 v[142:145], v248, s[14:15] offset:512
	s_waitcnt vmcnt(12)
	v_pk_fma_f32 v[62:63], v[216:217], v[62:63], v[146:147]
	v_pk_fma_f32 v[64:65], v[218:219], v[64:65], v[148:149]
	v_pk_fma_f32 v[46:47], v[216:217], v[46:47], v[150:151]
	v_pk_fma_f32 v[48:49], v[218:219], v[48:49], v[152:153]
	v_pk_fma_f32 v[30:31], v[216:217], v[30:31], v[154:155]
	v_pk_fma_f32 v[32:33], v[218:219], v[32:33], v[156:157]
	v_pk_fma_f32 v[14:15], v[216:217], v[14:15], v[158:159]
	v_pk_fma_f32 v[16:17], v[218:219], v[16:17], v[160:161]
	s_add_u32 s14, s10, 0x80000
	s_addc_u32 s15, s11, 0
	global_load_dwordx4 v[146:149], v248, s[14:15] offset:512
	s_add_u32 s14, s10, 0x90000
	s_addc_u32 s15, s11, 0
	global_load_dwordx4 v[150:153], v248, s[14:15] offset:512
	s_add_u32 s14, s10, 0xa0000
	s_addc_u32 s15, s11, 0
	global_load_dwordx4 v[154:157], v248, s[14:15] offset:512
	s_add_u32 s14, s10, 0xb0000
	s_addc_u32 s15, s11, 0
	global_load_dwordx4 v[158:161], v248, s[14:15] offset:512
	s_waitcnt vmcnt(12)
	v_pk_fma_f32 v[122:123], v[220:221], v[122:123], v[162:163]
	v_pk_fma_f32 v[124:125], v[222:223], v[124:125], v[164:165]
	v_pk_fma_f32 v[106:107], v[220:221], v[106:107], v[188:189]
	v_pk_fma_f32 v[108:109], v[222:223], v[108:109], v[190:191]
	v_pk_fma_f32 v[90:91], v[220:221], v[90:91], v[192:193]
	v_pk_fma_f32 v[92:93], v[222:223], v[92:93], v[194:195]
	v_pk_fma_f32 v[74:75], v[220:221], v[74:75], v[196:197]
	v_pk_fma_f32 v[76:77], v[222:223], v[76:77], v[198:199]
	global_load_dwordx4 v[162:165], v248, s[10:11] offset:576
	s_add_u32 s14, s10, 0x10000
	s_addc_u32 s15, s11, 0
	global_load_dwordx4 v[188:191], v248, s[14:15] offset:576
	s_add_u32 s14, s10, 0x20000
	s_addc_u32 s15, s11, 0
	global_load_dwordx4 v[192:195], v248, s[14:15] offset:576
	s_add_u32 s14, s10, 0x30000
	s_addc_u32 s15, s11, 0
	global_load_dwordx4 v[196:199], v248, s[14:15] offset:576
	s_waitcnt vmcnt(12)
	v_pk_fma_f32 v[58:59], v[220:221], v[58:59], v[200:201]
	v_pk_fma_f32 v[60:61], v[222:223], v[60:61], v[202:203]
	v_pk_fma_f32 v[42:43], v[220:221], v[42:43], v[204:205]
	v_pk_fma_f32 v[44:45], v[222:223], v[44:45], v[206:207]
	v_pk_fma_f32 v[26:27], v[220:221], v[26:27], v[208:209]
	v_pk_fma_f32 v[28:29], v[222:223], v[28:29], v[210:211]
	v_pk_fma_f32 v[10:11], v[220:221], v[10:11], v[212:213]
	v_pk_fma_f32 v[12:13], v[222:223], v[12:13], v[214:215]
	s_add_u32 s14, s10, 0x80000
	s_addc_u32 s15, s11, 0
	global_load_dwordx4 v[200:203], v248, s[14:15] offset:576
	s_add_u32 s14, s10, 0x90000
	s_addc_u32 s15, s11, 0
	global_load_dwordx4 v[204:207], v248, s[14:15] offset:576
	s_add_u32 s14, s10, 0xa0000
	s_addc_u32 s15, s11, 0
	global_load_dwordx4 v[208:211], v248, s[14:15] offset:576
	s_add_u32 s14, s10, 0xb0000
	s_addc_u32 s15, s11, 0
	global_load_dwordx4 v[212:215], v248, s[14:15] offset:576
	s_waitcnt vmcnt(12)
	v_pk_fma_f32 v[118:119], v[240:241], v[118:119], v[130:131]
	v_pk_fma_f32 v[120:121], v[242:243], v[120:121], v[132:133]
	v_pk_fma_f32 v[102:103], v[240:241], v[102:103], v[134:135]
	v_pk_fma_f32 v[104:105], v[242:243], v[104:105], v[136:137]
	v_pk_fma_f32 v[86:87], v[240:241], v[86:87], v[138:139]
	v_pk_fma_f32 v[88:89], v[242:243], v[88:89], v[140:141]
	v_pk_fma_f32 v[70:71], v[240:241], v[70:71], v[142:143]
	v_pk_fma_f32 v[72:73], v[242:243], v[72:73], v[144:145]
	s_waitcnt vmcnt(8)
	v_pk_fma_f32 v[54:55], v[240:241], v[54:55], v[146:147]
	v_pk_fma_f32 v[56:57], v[242:243], v[56:57], v[148:149]
	v_pk_fma_f32 v[38:39], v[240:241], v[38:39], v[150:151]
	v_pk_fma_f32 v[40:41], v[242:243], v[40:41], v[152:153]
	v_pk_fma_f32 v[22:23], v[240:241], v[22:23], v[154:155]
	v_pk_fma_f32 v[24:25], v[242:243], v[24:25], v[156:157]
	v_pk_fma_f32 v[6:7], v[240:241], v[6:7], v[158:159]
	v_pk_fma_f32 v[8:9], v[242:243], v[8:9], v[160:161]
	s_waitcnt vmcnt(4)
	v_pk_fma_f32 v[114:115], v[244:245], v[114:115], v[162:163]
	v_pk_fma_f32 v[116:117], v[246:247], v[116:117], v[164:165]
	v_pk_fma_f32 v[98:99], v[244:245], v[98:99], v[188:189]
	v_pk_fma_f32 v[100:101], v[246:247], v[100:101], v[190:191]
	v_pk_fma_f32 v[82:83], v[244:245], v[82:83], v[192:193]
	v_pk_fma_f32 v[84:85], v[246:247], v[84:85], v[194:195]
	v_pk_fma_f32 v[66:67], v[244:245], v[66:67], v[196:197]
	v_pk_fma_f32 v[68:69], v[246:247], v[68:69], v[198:199]
	s_waitcnt vmcnt(0)
	v_pk_fma_f32 v[50:51], v[244:245], v[50:51], v[200:201]
	v_pk_fma_f32 v[52:53], v[246:247], v[52:53], v[202:203]
	v_pk_fma_f32 v[34:35], v[244:245], v[34:35], v[204:205]
	v_pk_fma_f32 v[36:37], v[246:247], v[36:37], v[206:207]
	v_pk_fma_f32 v[18:19], v[244:245], v[18:19], v[208:209]
	v_pk_fma_f32 v[20:21], v[246:247], v[20:21], v[210:211]
	v_pk_fma_f32 v[2:3], v[244:245], v[2:3], v[212:213]
	v_pk_fma_f32 v[4:5], v[246:247], v[4:5], v[214:215]
	s_mov_b32 s2, s100
	s_mov_b64 s[100:101], s[12:13]
	s_cmp_eq_u32 s2, 99
	s_cbranch_scc1 .Lrf_finp
	s_ashr_i32 s8, s2, 2
	s_and_b32 s9, s2, 3
	s_mul_i32 s10, s8, 3
	s_add_i32 s11, s10, s9
	s_lshl_b32 s12, s17, 8
	s_sub_i32 s12, s12, 0x1800
	s_max_i32 s12, s12, 0
	s_lshr_b32 s12, s12, 11
	s_add_i32 s10, s10, s12
	s_mul_i32 s10, s10, 0x9000
	s_mul_i32 s9, s9, 0x3000
	s_add_i32 s10, s10, s9
	s_add_i32 s10, s10, 0x100000
	v_readlane_b32 s14, v255, 7
	v_readlane_b32 s15, v255, 8
	s_add_u32 s14, s14, s10
	s_addc_u32 s15, s15, 0
	s_add_u32 s12, s14, 0x1000
	s_addc_u32 s13, s15, 0
	v_readlane_b32 s8, v255, 14
	v_readlane_b32 s9, v255, 15
	s_load_dwordx2 s[8:9], s[8:9], 0x58
	s_lshl_b32 s11, s11, 12
	s_waitcnt lgkmcnt(0)
	s_add_u32 s8, s8, s11
	s_addc_u32 s9, s9, 0
	global_load_dwordx4 v[130:133], v250, s[8:9] offset:0
	global_load_dwordx4 v[146:149], v250, s[12:13] offset:0
	global_load_dwordx4 v[162:165], v250, s[14:15] offset:0
	global_load_dwordx4 v[134:137], v250, s[8:9] offset:64
	global_load_dwordx4 v[150:153], v250, s[12:13] offset:64
	global_load_dwordx4 v[188:191], v250, s[14:15] offset:64
	global_load_dwordx4 v[138:141], v250, s[8:9] offset:512
	global_load_dwordx4 v[154:157], v250, s[12:13] offset:512
	global_load_dwordx4 v[192:195], v250, s[14:15] offset:512
	global_load_dwordx4 v[142:145], v250, s[8:9] offset:576
	global_load_dwordx4 v[158:161], v250, s[12:13] offset:576
	global_load_dwordx4 v[196:199], v250, s[14:15] offset:576
	s_branch .Lrf_pdone
.Lrf_finp:
	v_readlane_b32 s8, v255, 14
	v_readlane_b32 s9, v255, 15
	s_load_dwordx2 s[8:9], s[8:9], 0x60
	s_waitcnt lgkmcnt(0)
	global_load_dwordx4 v[130:133], v250, s[8:9] offset:0
	global_load_dwordx4 v[134:137], v250, s[8:9] offset:64
	global_load_dwordx4 v[138:141], v250, s[8:9] offset:512
	global_load_dwordx4 v[142:145], v250, s[8:9] offset:576
.Lrf_pdone:
	v_mul_f32_e32 v200, v126, v126
	v_fmac_f32_e32 v200, v127, v127
	v_fmac_f32_e32 v200, v128, v128
	v_fmac_f32_e32 v200, v129, v129
	v_fmac_f32_e32 v200, v122, v122
	v_fmac_f32_e32 v200, v123, v123
	v_fmac_f32_e32 v200, v124, v124
	v_fmac_f32_e32 v200, v125, v125
	v_fmac_f32_e32 v200, v118, v118
	v_fmac_f32_e32 v200, v119, v119
	v_fmac_f32_e32 v200, v120, v120
	v_fmac_f32_e32 v200, v121, v121
	v_fmac_f32_e32 v200, v114, v114
	v_fmac_f32_e32 v200, v115, v115
	v_fmac_f32_e32 v200, v116, v116
	v_fmac_f32_e32 v200, v117, v117
	v_mul_f32_e32 v201, v110, v110
	v_fmac_f32_e32 v201, v111, v111
	v_fmac_f32_e32 v201, v112, v112
	v_fmac_f32_e32 v201, v113, v113
	v_fmac_f32_e32 v201, v106, v106
	v_fmac_f32_e32 v201, v107, v107
	v_fmac_f32_e32 v201, v108, v108
	v_fmac_f32_e32 v201, v109, v109
	v_fmac_f32_e32 v201, v102, v102
	v_fmac_f32_e32 v201, v103, v103
	v_fmac_f32_e32 v201, v104, v104
	v_fmac_f32_e32 v201, v105, v105
	v_fmac_f32_e32 v201, v98, v98
	v_fmac_f32_e32 v201, v99, v99
	v_fmac_f32_e32 v201, v100, v100
	v_fmac_f32_e32 v201, v101, v101
	v_mul_f32_e32 v202, v94, v94
	v_fmac_f32_e32 v202, v95, v95
	v_fmac_f32_e32 v202, v96, v96
	v_fmac_f32_e32 v202, v97, v97
	v_fmac_f32_e32 v202, v90, v90
	v_fmac_f32_e32 v202, v91, v91
	v_fmac_f32_e32 v202, v92, v92
	v_fmac_f32_e32 v202, v93, v93
	v_fmac_f32_e32 v202, v86, v86
	v_fmac_f32_e32 v202, v87, v87
	v_fmac_f32_e32 v202, v88, v88
	v_fmac_f32_e32 v202, v89, v89
	v_fmac_f32_e32 v202, v82, v82
	v_fmac_f32_e32 v202, v83, v83
	v_fmac_f32_e32 v202, v84, v84
	v_fmac_f32_e32 v202, v85, v85
	v_mul_f32_e32 v203, v78, v78
	v_fmac_f32_e32 v203, v79, v79
	v_fmac_f32_e32 v203, v80, v80
	v_fmac_f32_e32 v203, v81, v81
	v_fmac_f32_e32 v203, v74, v74
	v_fmac_f32_e32 v203, v75, v75
	v_fmac_f32_e32 v203, v76, v76
	v_fmac_f32_e32 v203, v77, v77
	v_fmac_f32_e32 v203, v70, v70
	v_fmac_f32_e32 v203, v71, v71
	v_fmac_f32_e32 v203, v72, v72
	v_fmac_f32_e32 v203, v73, v73
	v_fmac_f32_e32 v203, v66, v66
	v_fmac_f32_e32 v203, v67, v67
	v_fmac_f32_e32 v203, v68, v68
	v_fmac_f32_e32 v203, v69, v69
	v_mul_f32_e32 v204, v62, v62
	v_fmac_f32_e32 v204, v63, v63
	v_fmac_f32_e32 v204, v64, v64
	v_fmac_f32_e32 v204, v65, v65
	v_fmac_f32_e32 v204, v58, v58
	v_fmac_f32_e32 v204, v59, v59
	v_fmac_f32_e32 v204, v60, v60
	v_fmac_f32_e32 v204, v61, v61
	v_fmac_f32_e32 v204, v54, v54
	v_fmac_f32_e32 v204, v55, v55
	v_fmac_f32_e32 v204, v56, v56
	v_fmac_f32_e32 v204, v57, v57
	v_fmac_f32_e32 v204, v50, v50
	v_fmac_f32_e32 v204, v51, v51
	v_fmac_f32_e32 v204, v52, v52
	v_fmac_f32_e32 v204, v53, v53
	v_mul_f32_e32 v205, v46, v46
	v_fmac_f32_e32 v205, v47, v47
	v_fmac_f32_e32 v205, v48, v48
	v_fmac_f32_e32 v205, v49, v49
	v_fmac_f32_e32 v205, v42, v42
	v_fmac_f32_e32 v205, v43, v43
	v_fmac_f32_e32 v205, v44, v44
	v_fmac_f32_e32 v205, v45, v45
	v_fmac_f32_e32 v205, v38, v38
	v_fmac_f32_e32 v205, v39, v39
	v_fmac_f32_e32 v205, v40, v40
	v_fmac_f32_e32 v205, v41, v41
	v_fmac_f32_e32 v205, v34, v34
	v_fmac_f32_e32 v205, v35, v35
	v_fmac_f32_e32 v205, v36, v36
	v_fmac_f32_e32 v205, v37, v37
	v_mul_f32_e32 v206, v30, v30
	v_fmac_f32_e32 v206, v31, v31
	v_fmac_f32_e32 v206, v32, v32
	v_fmac_f32_e32 v206, v33, v33
	v_fmac_f32_e32 v206, v26, v26
	v_fmac_f32_e32 v206, v27, v27
	v_fmac_f32_e32 v206, v28, v28
	v_fmac_f32_e32 v206, v29, v29
	v_fmac_f32_e32 v206, v22, v22
	v_fmac_f32_e32 v206, v23, v23
	v_fmac_f32_e32 v206, v24, v24
	v_fmac_f32_e32 v206, v25, v25
	v_fmac_f32_e32 v206, v18, v18
	v_fmac_f32_e32 v206, v19, v19
	v_fmac_f32_e32 v206, v20, v20
	v_fmac_f32_e32 v206, v21, v21
	v_mul_f32_e32 v207, v14, v14
	v_fmac_f32_e32 v207, v15, v15
	v_fmac_f32_e32 v207, v16, v16
	v_fmac_f32_e32 v207, v17, v17
	v_fmac_f32_e32 v207, v10, v10
	v_fmac_f32_e32 v207, v11, v11
	v_fmac_f32_e32 v207, v12, v12
	v_fmac_f32_e32 v207, v13, v13
	v_fmac_f32_e32 v207, v6, v6
	v_fmac_f32_e32 v207, v7, v7
	v_fmac_f32_e32 v207, v8, v8
	v_fmac_f32_e32 v207, v9, v9
	v_fmac_f32_e32 v207, v2, v2
	v_fmac_f32_e32 v207, v3, v3
	v_fmac_f32_e32 v207, v4, v4
	v_fmac_f32_e32 v207, v5, v5
	v_mov_b32_e32 v208, v200
	v_mov_b32_e32 v209, v201
	v_mov_b32_e32 v210, v202
	v_mov_b32_e32 v211, v203
	v_mov_b32_e32 v212, v204
	v_mov_b32_e32 v213, v205
	v_mov_b32_e32 v214, v206
	v_mov_b32_e32 v215, v207
	s_nop 1
	v_permlane16_swap_b32_e32 v208, v200
	v_permlane16_swap_b32_e32 v209, v201
	v_permlane16_swap_b32_e32 v210, v202
	v_permlane16_swap_b32_e32 v211, v203
	v_permlane16_swap_b32_e32 v212, v204
	v_permlane16_swap_b32_e32 v213, v205
	v_permlane16_swap_b32_e32 v214, v206
	v_permlane16_swap_b32_e32 v215, v207
	v_add_f32_e32 v200, v200, v208
	v_add_f32_e32 v201, v201, v209
	v_add_f32_e32 v202, v202, v210
	v_add_f32_e32 v203, v203, v211
	v_add_f32_e32 v204, v204, v212
	v_add_f32_e32 v205, v205, v213
	v_add_f32_e32 v206, v206, v214
	v_add_f32_e32 v207, v207, v215
	v_mov_b32_e32 v208, v200
	v_mov_b32_e32 v209, v201
	v_mov_b32_e32 v210, v202
	v_mov_b32_e32 v211, v203
	v_mov_b32_e32 v212, v204
	v_mov_b32_e32 v213, v205
	v_mov_b32_e32 v214, v206
	v_mov_b32_e32 v215, v207
	s_nop 1
	v_permlane32_swap_b32_e32 v208, v200
	v_permlane32_swap_b32_e32 v209, v201
	v_permlane32_swap_b32_e32 v210, v202
	v_permlane32_swap_b32_e32 v211, v203
	v_permlane32_swap_b32_e32 v212, v204
	v_permlane32_swap_b32_e32 v213, v205
	v_permlane32_swap_b32_e32 v214, v206
	v_permlane32_swap_b32_e32 v215, v207
	v_add_f32_e32 v200, v200, v208
	v_add_f32_e32 v201, v201, v209
	v_add_f32_e32 v202, v202, v210
	v_add_f32_e32 v203, v203, v211
	v_add_f32_e32 v204, v204, v212
	v_add_f32_e32 v205, v205, v213
	v_add_f32_e32 v206, v206, v214
	v_add_f32_e32 v207, v207, v215
	v_readlane_b32 s3, v254, 63
	s_lshl_b32 s2, s3, 9
	s_add_i32 s2, s2, 0x20000
	v_lshlrev_b32_e32 v251, 2, v235
	v_add_u32_e32 v252, s2, v251
	ds_write_b32 v252, v200 offset:0
	ds_write_b32 v252, v201 offset:64
	ds_write_b32 v252, v202 offset:128
	ds_write_b32 v252, v203 offset:192
	ds_write_b32 v252, v204 offset:256
	ds_write_b32 v252, v205 offset:320
	ds_write_b32 v252, v206 offset:384
	ds_write_b32 v252, v207 offset:448
	s_lshl_b32 s2, s67, 5
	s_add_i32 s2, s2, 0x20000
	v_add_u32_e32 v252, s2, v251
	s_waitcnt lgkmcnt(0)
	s_barrier
	ds_read_b32 v216, v252 offset:0
	ds_read_b32 v217, v252 offset:512
	ds_read_b32 v218, v252 offset:1024
	ds_read_b32 v219, v252 offset:1536
	ds_read_b32 v220, v252 offset:64
	ds_read_b32 v221, v252 offset:576
	ds_read_b32 v222, v252 offset:1088
	ds_read_b32 v223, v252 offset:1600
	ds_read_b32 v240, v252 offset:128
	ds_read_b32 v241, v252 offset:640
	ds_read_b32 v242, v252 offset:1152
	ds_read_b32 v243, v252 offset:1664
	ds_read_b32 v244, v252 offset:192
	ds_read_b32 v245, v252 offset:704
	ds_read_b32 v246, v252 offset:1216
	ds_read_b32 v247, v252 offset:1728
	s_waitcnt lgkmcnt(0)
	v_add_f32_e32 v200, v216, v217
	v_add_f32_e32 v208, v218, v219
	v_add_f32_e32 v201, v220, v221
	v_add_f32_e32 v209, v222, v223
	v_add_f32_e32 v202, v240, v241
	v_add_f32_e32 v210, v242, v243
	v_add_f32_e32 v203, v244, v245
	v_add_f32_e32 v211, v246, v247
	v_add_f32_e32 v200, v200, v208
	v_add_f32_e32 v201, v201, v209
	v_add_f32_e32 v202, v202, v210
	v_add_f32_e32 v203, v203, v211
	ds_read_b32 v216, v252 offset:256
	ds_read_b32 v217, v252 offset:768
	ds_read_b32 v218, v252 offset:1280
	ds_read_b32 v219, v252 offset:1792
	ds_read_b32 v220, v252 offset:320
	ds_read_b32 v221, v252 offset:832
	ds_read_b32 v222, v252 offset:1344
	ds_read_b32 v223, v252 offset:1856
	ds_read_b32 v240, v252 offset:384
	ds_read_b32 v241, v252 offset:896
	ds_read_b32 v242, v252 offset:1408
	ds_read_b32 v243, v252 offset:1920
	ds_read_b32 v244, v252 offset:448
	ds_read_b32 v245, v252 offset:960
	ds_read_b32 v246, v252 offset:1472
	ds_read_b32 v247, v252 offset:1984
	s_waitcnt lgkmcnt(0)
	v_add_f32_e32 v204, v216, v217
	v_add_f32_e32 v212, v218, v219
	v_add_f32_e32 v205, v220, v221
	v_add_f32_e32 v213, v222, v223
	v_add_f32_e32 v206, v240, v241
	v_add_f32_e32 v214, v242, v243
	v_add_f32_e32 v207, v244, v245
	v_add_f32_e32 v215, v246, v247
	v_add_f32_e32 v204, v204, v212
	v_add_f32_e32 v205, v205, v213
	v_add_f32_e32 v206, v206, v214
	v_add_f32_e32 v207, v207, v215
	v_lshlrev_b32_e32 v253, 4, v186
	v_readlane_b32 s10, v255, 7
	v_readlane_b32 s11, v255, 8
	s_add_u32 s10, s10, 0x20000
	s_addc_u32 s11, s11, 0
	s_cmp_lg_u32 s68, 0
	s_cbranch_scc1 .Lrf_nopub
	s_lshl_b32 s2, s48, 2
	s_add_u32 s8, s10, s2
	s_addc_u32 s9, s11, 0
	s_mov_b64 s[14:15], exec
	s_mov_b64 exec, 0xffff
	global_store_dword v253, v200, s[8:9] offset:0
	global_store_dword v253, v201, s[8:9] offset:256
	global_store_dword v253, v202, s[8:9] offset:512
	global_store_dword v253, v203, s[8:9] offset:768
	global_store_dword v253, v204, s[8:9] offset:2048
	global_store_dword v253, v205, s[8:9] offset:2304
	global_store_dword v253, v206, s[8:9] offset:2560
	global_store_dword v253, v207, s[8:9] offset:2816
	s_mov_b64 exec, s[14:15]
.Lrf_nopub:
	v_readlane_b32 s8, v254, 61
	s_cmp_eq_u32 s8, 35
	s_cbranch_scc1 .Lrf_fin1
	s_nop 0
	global_store_dwordx4 v248, v[126:129], s[100:101] offset:0
	s_add_u32 s8, s100, 0x10000
	s_addc_u32 s9, s101, 0
	global_store_dwordx4 v248, v[110:113], s[8:9] offset:0
	s_add_u32 s8, s100, 0x20000
	s_addc_u32 s9, s101, 0
	global_store_dwordx4 v248, v[94:97], s[8:9] offset:0
	s_add_u32 s8, s100, 0x30000
	s_addc_u32 s9, s101, 0
	global_store_dwordx4 v248, v[78:81], s[8:9] offset:0
	s_add_u32 s8, s100, 0x80000
	s_addc_u32 s9, s101, 0
	global_store_dwordx4 v248, v[62:65], s[8:9] offset:0
	s_add_u32 s8, s100, 0x90000
	s_addc_u32 s9, s101, 0
	global_store_dwordx4 v248, v[46:49], s[8:9] offset:0
	s_add_u32 s8, s100, 0xa0000
	s_addc_u32 s9, s101, 0
	global_store_dwordx4 v248, v[30:33], s[8:9] offset:0
	s_add_u32 s8, s100, 0xb0000
	s_addc_u32 s9, s101, 0
	global_store_dwordx4 v248, v[14:17], s[8:9] offset:0
	global_store_dwordx4 v248, v[122:125], s[100:101] offset:64
	s_add_u32 s8, s100, 0x10000
	s_addc_u32 s9, s101, 0
	global_store_dwordx4 v248, v[106:109], s[8:9] offset:64
	s_add_u32 s8, s100, 0x20000
	s_addc_u32 s9, s101, 0
	global_store_dwordx4 v248, v[90:93], s[8:9] offset:64
	s_add_u32 s8, s100, 0x30000
	s_addc_u32 s9, s101, 0
	global_store_dwordx4 v248, v[74:77], s[8:9] offset:64
	s_add_u32 s8, s100, 0x80000
	s_addc_u32 s9, s101, 0
	global_store_dwordx4 v248, v[58:61], s[8:9] offset:64
	s_add_u32 s8, s100, 0x90000
	s_addc_u32 s9, s101, 0
	global_store_dwordx4 v248, v[42:45], s[8:9] offset:64
	s_add_u32 s8, s100, 0xa0000
	s_addc_u32 s9, s101, 0
	global_store_dwordx4 v248, v[26:29], s[8:9] offset:64
	s_add_u32 s8, s100, 0xb0000
	s_addc_u32 s9, s101, 0
	global_store_dwordx4 v248, v[10:13], s[8:9] offset:64
	global_store_dwordx4 v248, v[118:121], s[100:101] offset:512
	s_add_u32 s8, s100, 0x10000
	s_addc_u32 s9, s101, 0
	global_store_dwordx4 v248, v[102:105], s[8:9] offset:512
	s_add_u32 s8, s100, 0x20000
	s_addc_u32 s9, s101, 0
	global_store_dwordx4 v248, v[86:89], s[8:9] offset:512
	s_add_u32 s8, s100, 0x30000
	s_addc_u32 s9, s101, 0
	global_store_dwordx4 v248, v[70:73], s[8:9] offset:512
	s_add_u32 s8, s100, 0x80000
	s_addc_u32 s9, s101, 0
	global_store_dwordx4 v248, v[54:57], s[8:9] offset:512
	s_add_u32 s8, s100, 0x90000
	s_addc_u32 s9, s101, 0
	global_store_dwordx4 v248, v[38:41], s[8:9] offset:512
	s_add_u32 s8, s100, 0xa0000
	s_addc_u32 s9, s101, 0
	global_store_dwordx4 v248, v[22:25], s[8:9] offset:512
	s_add_u32 s8, s100, 0xb0000
	s_addc_u32 s9, s101, 0
	global_store_dwordx4 v248, v[6:9], s[8:9] offset:512
	global_store_dwordx4 v248, v[114:117], s[100:101] offset:576
	s_add_u32 s8, s100, 0x10000
	s_addc_u32 s9, s101, 0
	global_store_dwordx4 v248, v[98:101], s[8:9] offset:576
	s_add_u32 s8, s100, 0x20000
	s_addc_u32 s9, s101, 0
	global_store_dwordx4 v248, v[82:85], s[8:9] offset:576
	s_add_u32 s8, s100, 0x30000
	s_addc_u32 s9, s101, 0
	global_store_dwordx4 v248, v[66:69], s[8:9] offset:576
	s_add_u32 s8, s100, 0x80000
	s_addc_u32 s9, s101, 0
	global_store_dwordx4 v248, v[50:53], s[8:9] offset:576
	s_add_u32 s8, s100, 0x90000
	s_addc_u32 s9, s101, 0
	global_store_dwordx4 v248, v[34:37], s[8:9] offset:576
	s_add_u32 s8, s100, 0xa0000
	s_addc_u32 s9, s101, 0
	global_store_dwordx4 v248, v[18:21], s[8:9] offset:576
	s_add_u32 s8, s100, 0xb0000
	s_addc_u32 s9, s101, 0
	global_store_dwordx4 v248, v[2:5], s[8:9] offset:576
	s_waitcnt vmcnt(32)
	v_add_f32_e32 v146, 1.0, v146
	v_add_f32_e32 v147, 1.0, v147
	v_add_f32_e32 v148, 1.0, v148
	v_add_f32_e32 v149, 1.0, v149
	v_add_f32_e32 v150, 1.0, v150
	v_add_f32_e32 v151, 1.0, v151
	v_add_f32_e32 v152, 1.0, v152
	v_add_f32_e32 v153, 1.0, v153
	v_add_f32_e32 v154, 1.0, v154
	v_add_f32_e32 v155, 1.0, v155
	v_add_f32_e32 v156, 1.0, v156
	v_add_f32_e32 v157, 1.0, v157
	v_add_f32_e32 v158, 1.0, v158
	v_add_f32_e32 v159, 1.0, v159
	v_add_f32_e32 v160, 1.0, v160
	v_add_f32_e32 v161, 1.0, v161
	v_mul_f32_e32 v146, v130, v146
	v_mul_f32_e32 v147, v131, v147
	v_mul_f32_e32 v148, v132, v148
	v_mul_f32_e32 v149, v133, v149
	v_mul_f32_e32 v150, v134, v150
	v_mul_f32_e32 v151, v135, v151
	v_mul_f32_e32 v152, v136, v152
	v_mul_f32_e32 v153, v137, v153
	v_mul_f32_e32 v154, v138, v154
	v_mul_f32_e32 v155, v139, v155
	v_mul_f32_e32 v156, v140, v156
	v_mul_f32_e32 v157, v141, v157
	v_mul_f32_e32 v158, v142, v158
	v_mul_f32_e32 v159, v143, v159
	v_mul_f32_e32 v160, v144, v160
	v_mul_f32_e32 v161, v145, v161
	s_branch .Lrf_j1

.Lrf_j1:
	s_barrier
	s_cmp_lg_u32 s3, 0
	s_cbranch_scc1 .Lrf_bar
	v_readlane_b32 s2, v254, 61
	s_lshl_b32 s2, s2, 8
	s_lshl_b32 s8, s17, 2
	s_add_i32 s2, s2, s8
	s_add_i32 s2, s2, 0x10000
	v_readlane_b32 s8, v255, 7
	v_readlane_b32 s9, v255, 8
	s_add_u32 s8, s8, s2
	s_addc_u32 s9, s9, 0
	s_mov_b64 s[14:15], exec
	s_mov_b64 exec, 1
	global_atomic_add v1, v226, s[8:9]
	s_mov_b64 exec, s[14:15]
	s_mov_b32 s2, 0

.Lrf_bar:
	s_barrier
	global_load_dwordx4 v[200:203], v253, s[10:11] offset:0
	global_load_dwordx4 v[204:207], v253, s[10:11] offset:256
	global_load_dwordx4 v[208:211], v253, s[10:11] offset:512
	global_load_dwordx4 v[212:215], v253, s[10:11] offset:768
	global_load_dwordx4 v[216:219], v253, s[10:11] offset:2048
	global_load_dwordx4 v[220:223], v253, s[10:11] offset:2304
	global_load_dwordx4 v[240:243], v253, s[10:11] offset:2560
	global_load_dwordx4 v[244:247], v253, s[10:11] offset:2816
	v_lshl_add_u32 v251, v236, 2, s68
	v_lshlrev_b32_e32 v251, 1, v251
	v_add_u32_e32 v249, s67, v235
	v_mul_u32_u24_e32 v249, 0x210, v249
	v_add_u32_e32 v251, v251, v249
	v_add_u32_e32 v252, 0x10800, v251
	s_mov_b32 s2, 0x3a800000
	s_waitcnt vmcnt(7)
	v_add_f32_e32 v200, v200, v201
	v_add_f32_e32 v202, v202, v203
	v_add_f32_e32 v200, v200, v202
	v_fma_f32 v200, v200, s2, v167
	v_rsq_f32_e32 v200, v200
	s_waitcnt vmcnt(6)
	v_add_f32_e32 v204, v204, v205
	v_add_f32_e32 v206, v206, v207
	v_add_f32_e32 v204, v204, v206
	v_fma_f32 v204, v204, s2, v167
	v_rsq_f32_e32 v204, v204
	s_waitcnt vmcnt(5)
	v_add_f32_e32 v208, v208, v209
	v_add_f32_e32 v210, v210, v211
	v_add_f32_e32 v208, v208, v210
	v_fma_f32 v208, v208, s2, v167
	v_rsq_f32_e32 v208, v208
	s_waitcnt vmcnt(4)
	v_add_f32_e32 v212, v212, v213
	v_add_f32_e32 v214, v214, v215
	v_add_f32_e32 v212, v212, v214
	v_fma_f32 v212, v212, s2, v167
	v_rsq_f32_e32 v212, v212
	s_waitcnt vmcnt(3)
	v_add_f32_e32 v216, v216, v217
	v_add_f32_e32 v218, v218, v219
	v_add_f32_e32 v216, v216, v218
	v_fma_f32 v216, v216, s2, v167
	v_rsq_f32_e32 v216, v216
	s_waitcnt vmcnt(2)
	v_add_f32_e32 v220, v220, v221
	v_add_f32_e32 v222, v222, v223
	v_add_f32_e32 v220, v220, v222
	v_fma_f32 v220, v220, s2, v167
	v_rsq_f32_e32 v220, v220
	s_waitcnt vmcnt(1)
	v_add_f32_e32 v240, v240, v241
	v_add_f32_e32 v242, v242, v243
	v_add_f32_e32 v240, v240, v242
	v_fma_f32 v240, v240, s2, v167
	v_rsq_f32_e32 v240, v240
	s_waitcnt vmcnt(0)
	v_add_f32_e32 v244, v244, v245
	v_add_f32_e32 v246, v246, v247
	v_add_f32_e32 v244, v244, v246
	v_fma_f32 v244, v244, s2, v167
	v_rsq_f32_e32 v244, v244
	s_nop 0
	v_readlane_b32 s8, v254, 61
	s_cmp_eq_u32 s8, 35
	s_cbranch_scc1 .Lrf_fin2
	v_mul_f32_e32 v126, v126, v200
	v_mul_f32_e32 v127, v127, v200
	v_mul_f32_e32 v128, v128, v200
	v_mul_f32_e32 v129, v129, v200
	v_fma_f32 v126, v126, v146, v162
	v_fma_f32 v127, v127, v147, v163
	v_fma_f32 v128, v128, v148, v164
	v_fma_f32 v129, v129, v149, v165
	v_cvt_pk_bf16_f32 v126, v126, v127
	v_cvt_pk_bf16_f32 v127, v128, v129
	v_mul_f32_e32 v122, v122, v200
	v_mul_f32_e32 v123, v123, v200
	v_mul_f32_e32 v124, v124, v200
	v_mul_f32_e32 v125, v125, v200
	v_fma_f32 v122, v122, v150, v188
	v_fma_f32 v123, v123, v151, v189
	v_fma_f32 v124, v124, v152, v190
	v_fma_f32 v125, v125, v153, v191
	v_cvt_pk_bf16_f32 v122, v122, v123
	v_cvt_pk_bf16_f32 v123, v124, v125
	v_mul_f32_e32 v118, v118, v200
	v_mul_f32_e32 v119, v119, v200
	v_mul_f32_e32 v120, v120, v200
	v_mul_f32_e32 v121, v121, v200
	v_fma_f32 v118, v118, v154, v192
	v_fma_f32 v119, v119, v155, v193
	v_fma_f32 v120, v120, v156, v194
	v_fma_f32 v121, v121, v157, v195
	v_cvt_pk_bf16_f32 v118, v118, v119
	v_cvt_pk_bf16_f32 v119, v120, v121
	v_mul_f32_e32 v114, v114, v200
	v_mul_f32_e32 v115, v115, v200
	v_mul_f32_e32 v116, v116, v200
	v_mul_f32_e32 v117, v117, v200
	v_fma_f32 v114, v114, v158, v196
	v_fma_f32 v115, v115, v159, v197
	v_fma_f32 v116, v116, v160, v198
	v_fma_f32 v117, v117, v161, v199
	v_cvt_pk_bf16_f32 v114, v114, v115
	v_cvt_pk_bf16_f32 v115, v116, v117
	ds_write_b64 v251, v[126:127] offset:0
	ds_write_b64 v251, v[122:123] offset:32
	ds_write_b64 v251, v[118:119] offset:256
	ds_write_b64 v251, v[114:115] offset:288
	v_mul_f32_e32 v110, v110, v204
	v_mul_f32_e32 v111, v111, v204
	v_mul_f32_e32 v112, v112, v204
	v_mul_f32_e32 v113, v113, v204
	v_fma_f32 v110, v110, v146, v162
	v_fma_f32 v111, v111, v147, v163
	v_fma_f32 v112, v112, v148, v164
	v_fma_f32 v113, v113, v149, v165
	v_cvt_pk_bf16_f32 v110, v110, v111
	v_cvt_pk_bf16_f32 v111, v112, v113
	v_mul_f32_e32 v106, v106, v204
	v_mul_f32_e32 v107, v107, v204
	v_mul_f32_e32 v108, v108, v204
	v_mul_f32_e32 v109, v109, v204
	v_fma_f32 v106, v106, v150, v188
	v_fma_f32 v107, v107, v151, v189
	v_fma_f32 v108, v108, v152, v190
	v_fma_f32 v109, v109, v153, v191
	v_cvt_pk_bf16_f32 v106, v106, v107
	v_cvt_pk_bf16_f32 v107, v108, v109
	v_mul_f32_e32 v102, v102, v204
	v_mul_f32_e32 v103, v103, v204
	v_mul_f32_e32 v104, v104, v204
	v_mul_f32_e32 v105, v105, v204
	v_fma_f32 v102, v102, v154, v192
	v_fma_f32 v103, v103, v155, v193
	v_fma_f32 v104, v104, v156, v194
	v_fma_f32 v105, v105, v157, v195
	v_cvt_pk_bf16_f32 v102, v102, v103
	v_cvt_pk_bf16_f32 v103, v104, v105
	v_mul_f32_e32 v98, v98, v204
	v_mul_f32_e32 v99, v99, v204
	v_mul_f32_e32 v100, v100, v204
	v_mul_f32_e32 v101, v101, v204
	v_fma_f32 v98, v98, v158, v196
	v_fma_f32 v99, v99, v159, v197
	v_fma_f32 v100, v100, v160, v198
	v_fma_f32 v101, v101, v161, v199
	v_cvt_pk_bf16_f32 v98, v98, v99
	v_cvt_pk_bf16_f32 v99, v100, v101
	ds_write_b64 v251, v[110:111] offset:8448
	ds_write_b64 v251, v[106:107] offset:8480
	ds_write_b64 v251, v[102:103] offset:8704
	ds_write_b64 v251, v[98:99] offset:8736
	v_mul_f32_e32 v94, v94, v208
	v_mul_f32_e32 v95, v95, v208
	v_mul_f32_e32 v96, v96, v208
	v_mul_f32_e32 v97, v97, v208
	v_fma_f32 v94, v94, v146, v162
	v_fma_f32 v95, v95, v147, v163
	v_fma_f32 v96, v96, v148, v164
	v_fma_f32 v97, v97, v149, v165
	v_cvt_pk_bf16_f32 v94, v94, v95
	v_cvt_pk_bf16_f32 v95, v96, v97
	v_mul_f32_e32 v90, v90, v208
	v_mul_f32_e32 v91, v91, v208
	v_mul_f32_e32 v92, v92, v208
	v_mul_f32_e32 v93, v93, v208
	v_fma_f32 v90, v90, v150, v188
	v_fma_f32 v91, v91, v151, v189
	v_fma_f32 v92, v92, v152, v190
	v_fma_f32 v93, v93, v153, v191
	v_cvt_pk_bf16_f32 v90, v90, v91
	v_cvt_pk_bf16_f32 v91, v92, v93
	v_mul_f32_e32 v86, v86, v208
	v_mul_f32_e32 v87, v87, v208
	v_mul_f32_e32 v88, v88, v208
	v_mul_f32_e32 v89, v89, v208
	v_fma_f32 v86, v86, v154, v192
	v_fma_f32 v87, v87, v155, v193
	v_fma_f32 v88, v88, v156, v194
	v_fma_f32 v89, v89, v157, v195
	v_cvt_pk_bf16_f32 v86, v86, v87
	v_cvt_pk_bf16_f32 v87, v88, v89
	v_mul_f32_e32 v82, v82, v208
	v_mul_f32_e32 v83, v83, v208
	v_mul_f32_e32 v84, v84, v208
	v_mul_f32_e32 v85, v85, v208
	v_fma_f32 v82, v82, v158, v196
	v_fma_f32 v83, v83, v159, v197
	v_fma_f32 v84, v84, v160, v198
	v_fma_f32 v85, v85, v161, v199
	v_cvt_pk_bf16_f32 v82, v82, v83
	v_cvt_pk_bf16_f32 v83, v84, v85
	ds_write_b64 v251, v[94:95] offset:16896
	ds_write_b64 v251, v[90:91] offset:16928
	ds_write_b64 v251, v[86:87] offset:17152
	ds_write_b64 v251, v[82:83] offset:17184
	v_mul_f32_e32 v78, v78, v212
	v_mul_f32_e32 v79, v79, v212
	v_mul_f32_e32 v80, v80, v212
	v_mul_f32_e32 v81, v81, v212
	v_fma_f32 v78, v78, v146, v162
	v_fma_f32 v79, v79, v147, v163
	v_fma_f32 v80, v80, v148, v164
	v_fma_f32 v81, v81, v149, v165
	v_cvt_pk_bf16_f32 v78, v78, v79
	v_cvt_pk_bf16_f32 v79, v80, v81
	v_mul_f32_e32 v74, v74, v212
	v_mul_f32_e32 v75, v75, v212
	v_mul_f32_e32 v76, v76, v212
	v_mul_f32_e32 v77, v77, v212
	v_fma_f32 v74, v74, v150, v188
	v_fma_f32 v75, v75, v151, v189
	v_fma_f32 v76, v76, v152, v190
	v_fma_f32 v77, v77, v153, v191
	v_cvt_pk_bf16_f32 v74, v74, v75
	v_cvt_pk_bf16_f32 v75, v76, v77
	v_mul_f32_e32 v70, v70, v212
	v_mul_f32_e32 v71, v71, v212
	v_mul_f32_e32 v72, v72, v212
	v_mul_f32_e32 v73, v73, v212
	v_fma_f32 v70, v70, v154, v192
	v_fma_f32 v71, v71, v155, v193
	v_fma_f32 v72, v72, v156, v194
	v_fma_f32 v73, v73, v157, v195
	v_cvt_pk_bf16_f32 v70, v70, v71
	v_cvt_pk_bf16_f32 v71, v72, v73
	v_mul_f32_e32 v66, v66, v212
	v_mul_f32_e32 v67, v67, v212
	v_mul_f32_e32 v68, v68, v212
	v_mul_f32_e32 v69, v69, v212
	v_fma_f32 v66, v66, v158, v196
	v_fma_f32 v67, v67, v159, v197
	v_fma_f32 v68, v68, v160, v198
	v_fma_f32 v69, v69, v161, v199
	v_cvt_pk_bf16_f32 v66, v66, v67
	v_cvt_pk_bf16_f32 v67, v68, v69
	ds_write_b64 v251, v[78:79] offset:25344
	ds_write_b64 v251, v[74:75] offset:25376
	ds_write_b64 v251, v[70:71] offset:25600
	ds_write_b64 v251, v[66:67] offset:25632
	v_mul_f32_e32 v62, v62, v216
	v_mul_f32_e32 v63, v63, v216
	v_mul_f32_e32 v64, v64, v216
	v_mul_f32_e32 v65, v65, v216
	v_fma_f32 v62, v62, v146, v162
	v_fma_f32 v63, v63, v147, v163
	v_fma_f32 v64, v64, v148, v164
	v_fma_f32 v65, v65, v149, v165
	v_cvt_pk_bf16_f32 v62, v62, v63
	v_cvt_pk_bf16_f32 v63, v64, v65
	v_mul_f32_e32 v58, v58, v216
	v_mul_f32_e32 v59, v59, v216
	v_mul_f32_e32 v60, v60, v216
	v_mul_f32_e32 v61, v61, v216
	v_fma_f32 v58, v58, v150, v188
	v_fma_f32 v59, v59, v151, v189
	v_fma_f32 v60, v60, v152, v190
	v_fma_f32 v61, v61, v153, v191
	v_cvt_pk_bf16_f32 v58, v58, v59
	v_cvt_pk_bf16_f32 v59, v60, v61
	v_mul_f32_e32 v54, v54, v216
	v_mul_f32_e32 v55, v55, v216
	v_mul_f32_e32 v56, v56, v216
	v_mul_f32_e32 v57, v57, v216
	v_fma_f32 v54, v54, v154, v192
	v_fma_f32 v55, v55, v155, v193
	v_fma_f32 v56, v56, v156, v194
	v_fma_f32 v57, v57, v157, v195
	v_cvt_pk_bf16_f32 v54, v54, v55
	v_cvt_pk_bf16_f32 v55, v56, v57
	v_mul_f32_e32 v50, v50, v216
	v_mul_f32_e32 v51, v51, v216
	v_mul_f32_e32 v52, v52, v216
	v_mul_f32_e32 v53, v53, v216
	v_fma_f32 v50, v50, v158, v196
	v_fma_f32 v51, v51, v159, v197
	v_fma_f32 v52, v52, v160, v198
	v_fma_f32 v53, v53, v161, v199
	v_cvt_pk_bf16_f32 v50, v50, v51
	v_cvt_pk_bf16_f32 v51, v52, v53
	ds_write_b64 v252, v[62:63] offset:0
	ds_write_b64 v252, v[58:59] offset:32
	ds_write_b64 v252, v[54:55] offset:256
	ds_write_b64 v252, v[50:51] offset:288
	v_mul_f32_e32 v46, v46, v220
	v_mul_f32_e32 v47, v47, v220
	v_mul_f32_e32 v48, v48, v220
	v_mul_f32_e32 v49, v49, v220
	v_fma_f32 v46, v46, v146, v162
	v_fma_f32 v47, v47, v147, v163
	v_fma_f32 v48, v48, v148, v164
	v_fma_f32 v49, v49, v149, v165
	v_cvt_pk_bf16_f32 v46, v46, v47
	v_cvt_pk_bf16_f32 v47, v48, v49
	v_mul_f32_e32 v42, v42, v220
	v_mul_f32_e32 v43, v43, v220
	v_mul_f32_e32 v44, v44, v220
	v_mul_f32_e32 v45, v45, v220
	v_fma_f32 v42, v42, v150, v188
	v_fma_f32 v43, v43, v151, v189
	v_fma_f32 v44, v44, v152, v190
	v_fma_f32 v45, v45, v153, v191
	v_cvt_pk_bf16_f32 v42, v42, v43
	v_cvt_pk_bf16_f32 v43, v44, v45
	v_mul_f32_e32 v38, v38, v220
	v_mul_f32_e32 v39, v39, v220
	v_mul_f32_e32 v40, v40, v220
	v_mul_f32_e32 v41, v41, v220
	v_fma_f32 v38, v38, v154, v192
	v_fma_f32 v39, v39, v155, v193
	v_fma_f32 v40, v40, v156, v194
	v_fma_f32 v41, v41, v157, v195
	v_cvt_pk_bf16_f32 v38, v38, v39
	v_cvt_pk_bf16_f32 v39, v40, v41
	v_mul_f32_e32 v34, v34, v220
	v_mul_f32_e32 v35, v35, v220
	v_mul_f32_e32 v36, v36, v220
	v_mul_f32_e32 v37, v37, v220
	v_fma_f32 v34, v34, v158, v196
	v_fma_f32 v35, v35, v159, v197
	v_fma_f32 v36, v36, v160, v198
	v_fma_f32 v37, v37, v161, v199
	v_cvt_pk_bf16_f32 v34, v34, v35
	v_cvt_pk_bf16_f32 v35, v36, v37
	ds_write_b64 v252, v[46:47] offset:8448
	ds_write_b64 v252, v[42:43] offset:8480
	ds_write_b64 v252, v[38:39] offset:8704
	ds_write_b64 v252, v[34:35] offset:8736
	v_mul_f32_e32 v30, v30, v240
	v_mul_f32_e32 v31, v31, v240
	v_mul_f32_e32 v32, v32, v240
	v_mul_f32_e32 v33, v33, v240
	v_fma_f32 v30, v30, v146, v162
	v_fma_f32 v31, v31, v147, v163
	v_fma_f32 v32, v32, v148, v164
	v_fma_f32 v33, v33, v149, v165
	v_cvt_pk_bf16_f32 v30, v30, v31
	v_cvt_pk_bf16_f32 v31, v32, v33
	v_mul_f32_e32 v26, v26, v240
	v_mul_f32_e32 v27, v27, v240
	v_mul_f32_e32 v28, v28, v240
	v_mul_f32_e32 v29, v29, v240
	v_fma_f32 v26, v26, v150, v188
	v_fma_f32 v27, v27, v151, v189
	v_fma_f32 v28, v28, v152, v190
	v_fma_f32 v29, v29, v153, v191
	v_cvt_pk_bf16_f32 v26, v26, v27
	v_cvt_pk_bf16_f32 v27, v28, v29
	v_mul_f32_e32 v22, v22, v240
	v_mul_f32_e32 v23, v23, v240
	v_mul_f32_e32 v24, v24, v240
	v_mul_f32_e32 v25, v25, v240
	v_fma_f32 v22, v22, v154, v192
	v_fma_f32 v23, v23, v155, v193
	v_fma_f32 v24, v24, v156, v194
	v_fma_f32 v25, v25, v157, v195
	v_cvt_pk_bf16_f32 v22, v22, v23
	v_cvt_pk_bf16_f32 v23, v24, v25
	v_mul_f32_e32 v18, v18, v240
	v_mul_f32_e32 v19, v19, v240
	v_mul_f32_e32 v20, v20, v240
	v_mul_f32_e32 v21, v21, v240
	v_fma_f32 v18, v18, v158, v196
	v_fma_f32 v19, v19, v159, v197
	v_fma_f32 v20, v20, v160, v198
	v_fma_f32 v21, v21, v161, v199
	v_cvt_pk_bf16_f32 v18, v18, v19
	v_cvt_pk_bf16_f32 v19, v20, v21
	ds_write_b64 v252, v[30:31] offset:16896
	ds_write_b64 v252, v[26:27] offset:16928
	ds_write_b64 v252, v[22:23] offset:17152
	ds_write_b64 v252, v[18:19] offset:17184
	v_mul_f32_e32 v14, v14, v244
	v_mul_f32_e32 v15, v15, v244
	v_mul_f32_e32 v16, v16, v244
	v_mul_f32_e32 v17, v17, v244
	v_fma_f32 v14, v14, v146, v162
	v_fma_f32 v15, v15, v147, v163
	v_fma_f32 v16, v16, v148, v164
	v_fma_f32 v17, v17, v149, v165
	v_cvt_pk_bf16_f32 v14, v14, v15
	v_cvt_pk_bf16_f32 v15, v16, v17
	v_mul_f32_e32 v10, v10, v244
	v_mul_f32_e32 v11, v11, v244
	v_mul_f32_e32 v12, v12, v244
	v_mul_f32_e32 v13, v13, v244
	v_fma_f32 v10, v10, v150, v188
	v_fma_f32 v11, v11, v151, v189
	v_fma_f32 v12, v12, v152, v190
	v_fma_f32 v13, v13, v153, v191
	v_cvt_pk_bf16_f32 v10, v10, v11
	v_cvt_pk_bf16_f32 v11, v12, v13
	v_mul_f32_e32 v6, v6, v244
	v_mul_f32_e32 v7, v7, v244
	v_mul_f32_e32 v8, v8, v244
	v_mul_f32_e32 v9, v9, v244
	v_fma_f32 v6, v6, v154, v192
	v_fma_f32 v7, v7, v155, v193
	v_fma_f32 v8, v8, v156, v194
	v_fma_f32 v9, v9, v157, v195
	v_cvt_pk_bf16_f32 v6, v6, v7
	v_cvt_pk_bf16_f32 v7, v8, v9
	v_mul_f32_e32 v2, v2, v244
	v_mul_f32_e32 v3, v3, v244
	v_mul_f32_e32 v4, v4, v244
	v_mul_f32_e32 v5, v5, v244
	v_fma_f32 v2, v2, v158, v196
	v_fma_f32 v3, v3, v159, v197
	v_fma_f32 v4, v4, v160, v198
	v_fma_f32 v5, v5, v161, v199
	v_cvt_pk_bf16_f32 v2, v2, v3
	v_cvt_pk_bf16_f32 v3, v4, v5
	ds_write_b64 v252, v[14:15] offset:25344
	ds_write_b64 v252, v[10:11] offset:25376
	ds_write_b64 v252, v[6:7] offset:25600
	ds_write_b64 v252, v[2:3] offset:25632
	v_lshl_add_u32 v249, v236, 4, v235
	v_lshrrev_b32_e32 v250, 5, v249
	v_and_b32_e32 v249, 31, v249
	v_lshlrev_b32_e32 v249, 4, v249
	v_lshl_add_u32 v250, s3, 5, v250
	v_mul_u32_u24_e32 v251, 0x210, v250
	v_add_u32_e32 v251, v251, v249
	v_lshl_add_u32 v248, v250, 11, v249
	v_readlane_b32 s12, v255, 9
	v_readlane_b32 s13, v255, 10
	s_lshl_b32 s2, s17, 19
	s_lshl_b32 s8, s48, 9
	s_add_i32 s2, s2, s8
	s_add_u32 s12, s12, s2
	s_addc_u32 s13, s13, 0
	s_waitcnt lgkmcnt(0)
	s_barrier
	ds_read_b128 v[2:5], v251 offset:0
	ds_read_b128 v[6:9], v251 offset:1056
	ds_read_b128 v[10:13], v251 offset:2112
	ds_read_b128 v[14:17], v251 offset:3168
	ds_read_b128 v[18:21], v251 offset:4224
	ds_read_b128 v[22:25], v251 offset:5280
	ds_read_b128 v[26:29], v251 offset:6336
	ds_read_b128 v[30:33], v251 offset:7392
	ds_read_b128 v[34:37], v251 offset:8448
	ds_read_b128 v[38:41], v251 offset:9504
	ds_read_b128 v[42:45], v251 offset:10560
	ds_read_b128 v[46:49], v251 offset:11616
	ds_read_b128 v[50:53], v251 offset:12672
	ds_read_b128 v[54:57], v251 offset:13728
	ds_read_b128 v[58:61], v251 offset:14784
	ds_read_b128 v[62:65], v251 offset:15840
	s_waitcnt lgkmcnt(15)
	global_store_dwordx4 v248, v[2:5], s[12:13]
	s_waitcnt lgkmcnt(14)
	s_add_u32 s14, s12, 0x1000
	s_addc_u32 s15, s13, 0
	global_store_dwordx4 v248, v[6:9], s[14:15]
	s_waitcnt lgkmcnt(13)
	s_add_u32 s14, s12, 0x2000
	s_addc_u32 s15, s13, 0
	global_store_dwordx4 v248, v[10:13], s[14:15]
	s_waitcnt lgkmcnt(12)
	s_add_u32 s14, s12, 0x3000
	s_addc_u32 s15, s13, 0
	global_store_dwordx4 v248, v[14:17], s[14:15]
	s_waitcnt lgkmcnt(11)
	s_add_u32 s14, s12, 0x4000
	s_addc_u32 s15, s13, 0
	global_store_dwordx4 v248, v[18:21], s[14:15]
	s_waitcnt lgkmcnt(10)
	s_add_u32 s14, s12, 0x5000
	s_addc_u32 s15, s13, 0
	global_store_dwordx4 v248, v[22:25], s[14:15]
	s_waitcnt lgkmcnt(9)
	s_add_u32 s14, s12, 0x6000
	s_addc_u32 s15, s13, 0
	global_store_dwordx4 v248, v[26:29], s[14:15]
	s_waitcnt lgkmcnt(8)
	s_add_u32 s14, s12, 0x7000
	s_addc_u32 s15, s13, 0
	global_store_dwordx4 v248, v[30:33], s[14:15]
	s_waitcnt lgkmcnt(7)
	s_add_u32 s14, s12, 0x8000
	s_addc_u32 s15, s13, 0
	global_store_dwordx4 v248, v[34:37], s[14:15]
	s_waitcnt lgkmcnt(6)
	s_add_u32 s14, s12, 0x9000
	s_addc_u32 s15, s13, 0
	global_store_dwordx4 v248, v[38:41], s[14:15]
	s_waitcnt lgkmcnt(5)
	s_add_u32 s14, s12, 0xa000
	s_addc_u32 s15, s13, 0
	global_store_dwordx4 v248, v[42:45], s[14:15]
	s_waitcnt lgkmcnt(4)
	s_add_u32 s14, s12, 0xb000
	s_addc_u32 s15, s13, 0
	global_store_dwordx4 v248, v[46:49], s[14:15]
	s_waitcnt lgkmcnt(3)
	s_add_u32 s14, s12, 0xc000
	s_addc_u32 s15, s13, 0
	global_store_dwordx4 v248, v[50:53], s[14:15]
	s_waitcnt lgkmcnt(2)
	s_add_u32 s14, s12, 0xd000
	s_addc_u32 s15, s13, 0
	global_store_dwordx4 v248, v[54:57], s[14:15]
	s_waitcnt lgkmcnt(1)
	s_add_u32 s14, s12, 0xe000
	s_addc_u32 s15, s13, 0
	global_store_dwordx4 v248, v[58:61], s[14:15]
	s_waitcnt lgkmcnt(0)
	s_add_u32 s14, s12, 0xf000
	s_addc_u32 s15, s13, 0
	global_store_dwordx4 v248, v[62:65], s[14:15]
	s_branch .LBB0_561
.Lrf_fin2:
	v_mul_f32_e32 v126, v126, v200
	v_mul_f32_e32 v127, v127, v200
	v_mul_f32_e32 v128, v128, v200
	v_mul_f32_e32 v129, v129, v200
	v_mul_f32_e32 v126, v126, v130
	v_mul_f32_e32 v127, v127, v131
	v_mul_f32_e32 v128, v128, v132
	v_mul_f32_e32 v129, v129, v133
	v_mul_f32_e32 v122, v122, v200
	v_mul_f32_e32 v123, v123, v200
	v_mul_f32_e32 v124, v124, v200
	v_mul_f32_e32 v125, v125, v200
	v_mul_f32_e32 v122, v122, v134
	v_mul_f32_e32 v123, v123, v135
	v_mul_f32_e32 v124, v124, v136
	v_mul_f32_e32 v125, v125, v137
	v_mul_f32_e32 v118, v118, v200
	v_mul_f32_e32 v119, v119, v200
	v_mul_f32_e32 v120, v120, v200
	v_mul_f32_e32 v121, v121, v200
	v_mul_f32_e32 v118, v118, v138
	v_mul_f32_e32 v119, v119, v139
	v_mul_f32_e32 v120, v120, v140
	v_mul_f32_e32 v121, v121, v141
	v_mul_f32_e32 v114, v114, v200
	v_mul_f32_e32 v115, v115, v200
	v_mul_f32_e32 v116, v116, v200
	v_mul_f32_e32 v117, v117, v200
	v_mul_f32_e32 v114, v114, v142
	v_mul_f32_e32 v115, v115, v143
	v_mul_f32_e32 v116, v116, v144
	v_mul_f32_e32 v117, v117, v145
	global_store_dwordx4 v248, v[126:129], s[100:101] offset:0
	global_store_dwordx4 v248, v[122:125], s[100:101] offset:64
	global_store_dwordx4 v248, v[118:121], s[100:101] offset:512
	global_store_dwordx4 v248, v[114:117], s[100:101] offset:576
	s_add_u32 s8, s100, 0x10000
	s_addc_u32 s9, s101, 0
	v_mul_f32_e32 v110, v110, v204
	v_mul_f32_e32 v111, v111, v204
	v_mul_f32_e32 v112, v112, v204
	v_mul_f32_e32 v113, v113, v204
	v_mul_f32_e32 v110, v110, v130
	v_mul_f32_e32 v111, v111, v131
	v_mul_f32_e32 v112, v112, v132
	v_mul_f32_e32 v113, v113, v133
	v_mul_f32_e32 v106, v106, v204
	v_mul_f32_e32 v107, v107, v204
	v_mul_f32_e32 v108, v108, v204
	v_mul_f32_e32 v109, v109, v204
	v_mul_f32_e32 v106, v106, v134
	v_mul_f32_e32 v107, v107, v135
	v_mul_f32_e32 v108, v108, v136
	v_mul_f32_e32 v109, v109, v137
	v_mul_f32_e32 v102, v102, v204
	v_mul_f32_e32 v103, v103, v204
	v_mul_f32_e32 v104, v104, v204
	v_mul_f32_e32 v105, v105, v204
	v_mul_f32_e32 v102, v102, v138
	v_mul_f32_e32 v103, v103, v139
	v_mul_f32_e32 v104, v104, v140
	v_mul_f32_e32 v105, v105, v141
	v_mul_f32_e32 v98, v98, v204
	v_mul_f32_e32 v99, v99, v204
	v_mul_f32_e32 v100, v100, v204
	v_mul_f32_e32 v101, v101, v204
	v_mul_f32_e32 v98, v98, v142
	v_mul_f32_e32 v99, v99, v143
	v_mul_f32_e32 v100, v100, v144
	v_mul_f32_e32 v101, v101, v145
	global_store_dwordx4 v248, v[110:113], s[8:9] offset:0
	global_store_dwordx4 v248, v[106:109], s[8:9] offset:64
	global_store_dwordx4 v248, v[102:105], s[8:9] offset:512
	global_store_dwordx4 v248, v[98:101], s[8:9] offset:576
	s_add_u32 s8, s100, 0x20000
	s_addc_u32 s9, s101, 0
	v_mul_f32_e32 v94, v94, v208
	v_mul_f32_e32 v95, v95, v208
	v_mul_f32_e32 v96, v96, v208
	v_mul_f32_e32 v97, v97, v208
	v_mul_f32_e32 v94, v94, v130
	v_mul_f32_e32 v95, v95, v131
	v_mul_f32_e32 v96, v96, v132
	v_mul_f32_e32 v97, v97, v133
	v_mul_f32_e32 v90, v90, v208
	v_mul_f32_e32 v91, v91, v208
	v_mul_f32_e32 v92, v92, v208
	v_mul_f32_e32 v93, v93, v208
	v_mul_f32_e32 v90, v90, v134
	v_mul_f32_e32 v91, v91, v135
	v_mul_f32_e32 v92, v92, v136
	v_mul_f32_e32 v93, v93, v137
	v_mul_f32_e32 v86, v86, v208
	v_mul_f32_e32 v87, v87, v208
	v_mul_f32_e32 v88, v88, v208
	v_mul_f32_e32 v89, v89, v208
	v_mul_f32_e32 v86, v86, v138
	v_mul_f32_e32 v87, v87, v139
	v_mul_f32_e32 v88, v88, v140
	v_mul_f32_e32 v89, v89, v141
	v_mul_f32_e32 v82, v82, v208
	v_mul_f32_e32 v83, v83, v208
	v_mul_f32_e32 v84, v84, v208
	v_mul_f32_e32 v85, v85, v208
	v_mul_f32_e32 v82, v82, v142
	v_mul_f32_e32 v83, v83, v143
	v_mul_f32_e32 v84, v84, v144
	v_mul_f32_e32 v85, v85, v145
	global_store_dwordx4 v248, v[94:97], s[8:9] offset:0
	global_store_dwordx4 v248, v[90:93], s[8:9] offset:64
	global_store_dwordx4 v248, v[86:89], s[8:9] offset:512
	global_store_dwordx4 v248, v[82:85], s[8:9] offset:576
	s_add_u32 s8, s100, 0x30000
	s_addc_u32 s9, s101, 0
	v_mul_f32_e32 v78, v78, v212
	v_mul_f32_e32 v79, v79, v212
	v_mul_f32_e32 v80, v80, v212
	v_mul_f32_e32 v81, v81, v212
	v_mul_f32_e32 v78, v78, v130
	v_mul_f32_e32 v79, v79, v131
	v_mul_f32_e32 v80, v80, v132
	v_mul_f32_e32 v81, v81, v133
	v_mul_f32_e32 v74, v74, v212
	v_mul_f32_e32 v75, v75, v212
	v_mul_f32_e32 v76, v76, v212
	v_mul_f32_e32 v77, v77, v212
	v_mul_f32_e32 v74, v74, v134
	v_mul_f32_e32 v75, v75, v135
	v_mul_f32_e32 v76, v76, v136
	v_mul_f32_e32 v77, v77, v137
	v_mul_f32_e32 v70, v70, v212
	v_mul_f32_e32 v71, v71, v212
	v_mul_f32_e32 v72, v72, v212
	v_mul_f32_e32 v73, v73, v212
	v_mul_f32_e32 v70, v70, v138
	v_mul_f32_e32 v71, v71, v139
	v_mul_f32_e32 v72, v72, v140
	v_mul_f32_e32 v73, v73, v141
	v_mul_f32_e32 v66, v66, v212
	v_mul_f32_e32 v67, v67, v212
	v_mul_f32_e32 v68, v68, v212
	v_mul_f32_e32 v69, v69, v212
	v_mul_f32_e32 v66, v66, v142
	v_mul_f32_e32 v67, v67, v143
	v_mul_f32_e32 v68, v68, v144
	v_mul_f32_e32 v69, v69, v145
	global_store_dwordx4 v248, v[78:81], s[8:9] offset:0
	global_store_dwordx4 v248, v[74:77], s[8:9] offset:64
	global_store_dwordx4 v248, v[70:73], s[8:9] offset:512
	global_store_dwordx4 v248, v[66:69], s[8:9] offset:576
	s_add_u32 s8, s100, 0x80000
	s_addc_u32 s9, s101, 0
	v_mul_f32_e32 v62, v62, v216
	v_mul_f32_e32 v63, v63, v216
	v_mul_f32_e32 v64, v64, v216
	v_mul_f32_e32 v65, v65, v216
	v_mul_f32_e32 v62, v62, v130
	v_mul_f32_e32 v63, v63, v131
	v_mul_f32_e32 v64, v64, v132
	v_mul_f32_e32 v65, v65, v133
	v_mul_f32_e32 v58, v58, v216
	v_mul_f32_e32 v59, v59, v216
	v_mul_f32_e32 v60, v60, v216
	v_mul_f32_e32 v61, v61, v216
	v_mul_f32_e32 v58, v58, v134
	v_mul_f32_e32 v59, v59, v135
	v_mul_f32_e32 v60, v60, v136
	v_mul_f32_e32 v61, v61, v137
	v_mul_f32_e32 v54, v54, v216
	v_mul_f32_e32 v55, v55, v216
	v_mul_f32_e32 v56, v56, v216
	v_mul_f32_e32 v57, v57, v216
	v_mul_f32_e32 v54, v54, v138
	v_mul_f32_e32 v55, v55, v139
	v_mul_f32_e32 v56, v56, v140
	v_mul_f32_e32 v57, v57, v141
	v_mul_f32_e32 v50, v50, v216
	v_mul_f32_e32 v51, v51, v216
	v_mul_f32_e32 v52, v52, v216
	v_mul_f32_e32 v53, v53, v216
	v_mul_f32_e32 v50, v50, v142
	v_mul_f32_e32 v51, v51, v143
	v_mul_f32_e32 v52, v52, v144
	v_mul_f32_e32 v53, v53, v145
	global_store_dwordx4 v248, v[62:65], s[8:9] offset:0
	global_store_dwordx4 v248, v[58:61], s[8:9] offset:64
	global_store_dwordx4 v248, v[54:57], s[8:9] offset:512
	global_store_dwordx4 v248, v[50:53], s[8:9] offset:576
	s_add_u32 s8, s100, 0x90000
	s_addc_u32 s9, s101, 0
	v_mul_f32_e32 v46, v46, v220
	v_mul_f32_e32 v47, v47, v220
	v_mul_f32_e32 v48, v48, v220
	v_mul_f32_e32 v49, v49, v220
	v_mul_f32_e32 v46, v46, v130
	v_mul_f32_e32 v47, v47, v131
	v_mul_f32_e32 v48, v48, v132
	v_mul_f32_e32 v49, v49, v133
	v_mul_f32_e32 v42, v42, v220
	v_mul_f32_e32 v43, v43, v220
	v_mul_f32_e32 v44, v44, v220
	v_mul_f32_e32 v45, v45, v220
	v_mul_f32_e32 v42, v42, v134
	v_mul_f32_e32 v43, v43, v135
	v_mul_f32_e32 v44, v44, v136
	v_mul_f32_e32 v45, v45, v137
	v_mul_f32_e32 v38, v38, v220
	v_mul_f32_e32 v39, v39, v220
	v_mul_f32_e32 v40, v40, v220
	v_mul_f32_e32 v41, v41, v220
	v_mul_f32_e32 v38, v38, v138
	v_mul_f32_e32 v39, v39, v139
	v_mul_f32_e32 v40, v40, v140
	v_mul_f32_e32 v41, v41, v141
	v_mul_f32_e32 v34, v34, v220
	v_mul_f32_e32 v35, v35, v220
	v_mul_f32_e32 v36, v36, v220
	v_mul_f32_e32 v37, v37, v220
	v_mul_f32_e32 v34, v34, v142
	v_mul_f32_e32 v35, v35, v143
	v_mul_f32_e32 v36, v36, v144
	v_mul_f32_e32 v37, v37, v145
	global_store_dwordx4 v248, v[46:49], s[8:9] offset:0
	global_store_dwordx4 v248, v[42:45], s[8:9] offset:64
	global_store_dwordx4 v248, v[38:41], s[8:9] offset:512
	global_store_dwordx4 v248, v[34:37], s[8:9] offset:576
	s_add_u32 s8, s100, 0xa0000
	s_addc_u32 s9, s101, 0
	v_mul_f32_e32 v30, v30, v240
	v_mul_f32_e32 v31, v31, v240
	v_mul_f32_e32 v32, v32, v240
	v_mul_f32_e32 v33, v33, v240
	v_mul_f32_e32 v30, v30, v130
	v_mul_f32_e32 v31, v31, v131
	v_mul_f32_e32 v32, v32, v132
	v_mul_f32_e32 v33, v33, v133
	v_mul_f32_e32 v26, v26, v240
	v_mul_f32_e32 v27, v27, v240
	v_mul_f32_e32 v28, v28, v240
	v_mul_f32_e32 v29, v29, v240
	v_mul_f32_e32 v26, v26, v134
	v_mul_f32_e32 v27, v27, v135
	v_mul_f32_e32 v28, v28, v136
	v_mul_f32_e32 v29, v29, v137
	v_mul_f32_e32 v22, v22, v240
	v_mul_f32_e32 v23, v23, v240
	v_mul_f32_e32 v24, v24, v240
	v_mul_f32_e32 v25, v25, v240
	v_mul_f32_e32 v22, v22, v138
	v_mul_f32_e32 v23, v23, v139
	v_mul_f32_e32 v24, v24, v140
	v_mul_f32_e32 v25, v25, v141
	v_mul_f32_e32 v18, v18, v240
	v_mul_f32_e32 v19, v19, v240
	v_mul_f32_e32 v20, v20, v240
	v_mul_f32_e32 v21, v21, v240
	v_mul_f32_e32 v18, v18, v142
	v_mul_f32_e32 v19, v19, v143
	v_mul_f32_e32 v20, v20, v144
	v_mul_f32_e32 v21, v21, v145
	global_store_dwordx4 v248, v[30:33], s[8:9] offset:0
	global_store_dwordx4 v248, v[26:29], s[8:9] offset:64
	global_store_dwordx4 v248, v[22:25], s[8:9] offset:512
	global_store_dwordx4 v248, v[18:21], s[8:9] offset:576
	s_add_u32 s8, s100, 0xb0000
	s_addc_u32 s9, s101, 0
	v_mul_f32_e32 v14, v14, v244
	v_mul_f32_e32 v15, v15, v244
	v_mul_f32_e32 v16, v16, v244
	v_mul_f32_e32 v17, v17, v244
	v_mul_f32_e32 v14, v14, v130
	v_mul_f32_e32 v15, v15, v131
	v_mul_f32_e32 v16, v16, v132
	v_mul_f32_e32 v17, v17, v133
	v_mul_f32_e32 v10, v10, v244
	v_mul_f32_e32 v11, v11, v244
	v_mul_f32_e32 v12, v12, v244
	v_mul_f32_e32 v13, v13, v244
	v_mul_f32_e32 v10, v10, v134
	v_mul_f32_e32 v11, v11, v135
	v_mul_f32_e32 v12, v12, v136
	v_mul_f32_e32 v13, v13, v137
	v_mul_f32_e32 v6, v6, v244
	v_mul_f32_e32 v7, v7, v244
	v_mul_f32_e32 v8, v8, v244
	v_mul_f32_e32 v9, v9, v244
	v_mul_f32_e32 v6, v6, v138
	v_mul_f32_e32 v7, v7, v139
	v_mul_f32_e32 v8, v8, v140
	v_mul_f32_e32 v9, v9, v141
	v_mul_f32_e32 v2, v2, v244
	v_mul_f32_e32 v3, v3, v244
	v_mul_f32_e32 v4, v4, v244
	v_mul_f32_e32 v5, v5, v244
	v_mul_f32_e32 v2, v2, v142
	v_mul_f32_e32 v3, v3, v143
	v_mul_f32_e32 v4, v4, v144
	v_mul_f32_e32 v5, v5, v145
	global_store_dwordx4 v248, v[14:17], s[8:9] offset:0
	global_store_dwordx4 v248, v[10:13], s[8:9] offset:64
	global_store_dwordx4 v248, v[6:9], s[8:9] offset:512
	global_store_dwordx4 v248, v[2:5], s[8:9] offset:576
	s_branch .LBB0_561

PROG:
	.byte	0, 0, 1
	.byte	1, 0, 1
	.byte	3, 0, 1
	.byte	4, 0, 1
	.byte	1, 1, 1
	.byte	5, 0, 1
	.byte	6, 0, 1
	.byte	7, 0, 1
	.byte	8, 0, 1
	.byte	3, 1, 1
	.byte	4, 1, 1
	.byte	3, 2, 1
	.byte	4, 2, 1
	.byte	2, 5, 1
	.byte	9, 0, 0
	.byte	10, 0, 1
	.byte	11, 0, 1
	.byte	8, 1, 0
	.byte	1, 6, 1
	.byte	3, 3, 1
	.byte	4, 3, 1
	.byte	3, 4, 1
	.byte	4, 4, 1
	.byte	12, 0, 1
	.byte	13, 0, 1
	.byte	14, 0, 1
	.byte	8, 2, 1
	.byte	3, 5, 1
	.byte	4, 5, 1
	.byte	3, 6, 1
	.byte	4, 6, 1
	.byte	15, 0, 1
	.byte	16, 0, 1
	.byte	8, 3, 1
	.byte	3, 7, 1
	.byte	4, 7, 0
	.size	PROG, 108

	.protected	BGTAB
	.type	BGTAB,@object
	.globl	BGTAB
	.p2align	4, 0x0
BGTAB:
	.long	0, 0, 0, 0
	.long	0, 0, 0, 0
	.long	2816, 8448, 0, 0
	.long	8448, 12672, 33792, 36352
	.long	0, 0, 0, 0
	.long	0, 0, 0, 0
	.long	0, 0, 0, 0
	.long	0, 0, 0, 0
	.long	0, 0, 0, 0
	.long	12672, 16896, 36352, 36864
	.long	16896, 21120, 40448, 40960
	.long	21120, 25344, 36864, 38400
	.long	25344, 29568, 0, 0
	.long	0, 0, 0, 0
	.long	0, 0, 0, 0
	.long	0, 0, 0, 0
	.long	0, 0, 0, 0
	.long	0, 0, 0, 0
	.long	0, 0, 0, 0
	.long	29568, 33792, 38400, 40448
	.long	0, 0, 0, 0
	.long	0, 0, 0, 0
	.long	0, 0, 0, 0
	.long	0, 0, 0, 0
	.long	0, 0, 0, 0
	.long	0, 0, 0, 0
	.long	0, 0, 0, 0
	.long	0, 0, 0, 0
	.long	0, 0, 0, 0
	.long	0, 0, 0, 0
	.long	0, 0, 0, 0
	.long	0, 0, 0, 0
	.long	0, 0, 0, 0
	.long	0, 0, 0, 0
	.long	0, 0, 0, 0
	.long	0, 0, 0, 0
	.size	BGTAB, 576

	.type	__hip_cuid_dfa6192372e94434,@object
